# prologue residual-row conversion: 4 row loads issued together, next row prefetched, scalar source addressing without per-row kernarg reloads, on top of v11
# speedup vs baseline: 1.0059x; 1.0059x over previous
; DI unsigned pk2(float lo, float hi) { unsigned r; asm volatile("v_cvt_pk_bf16_f32 %0, %1, %2" : "=v"(r) : "v"(lo), "v"(hi)); return r; }
; DI void phase_prologue(const Prm& p, LAS unsigned char* lds, int tid, int lane, int wave) {
;     const int gw = blockIdx.x * 8 + wave, NGW = gridDim.x * 8, gtid = blockIdx.x * 512 + tid, GT = gridDim.x * 512;
;     ...
;     for (int row = gw; row < NT; row += NGW) {
;         const float* src;
;         if (row < NTP) { const int b = row / TP, t = row - b * TP; src = t < 16 ? p.meta + (size_t)t * 1024 : p.x_prompt + ((size_t)b * 4096 + (t - 16)) * 1024; }
;         else src = p.x_sample + (size_t)(row - NTP) * 1024;
;         float ss = 0.f;
; #pragma unroll
;         for (int j = 0; j < 4; ++j) { const f32x4 v = ((const f32x4*)src)[lane + 64 * j]; u32x2 o; o.x = pk2(v.x, v.y); o.y = pk2(v.z, v.w);
.LBB0_76:
	s_cmp_lg_u32 s98, 0
	s_cbranch_scc1 .Ltr_return
	s_load_dwordx16 s[36:51], s[0:1], 0x0
	v_lshlrev_b32_e32 v2, 2, v152
	v_lshlrev_b32_e32 v156, 3, v152
	s_waitcnt lgkmcnt(0)
	v_writelane_b32 v254, s36, 54
	s_nop 1
	v_writelane_b32 v254, s37, 55
	v_writelane_b32 v254, s38, 56
	v_writelane_b32 v254, s39, 57
	v_writelane_b32 v254, s40, 58
	v_writelane_b32 v254, s41, 59
	v_writelane_b32 v254, s42, 60
	v_writelane_b32 v255, s46, 0
	v_writelane_b32 v254, s43, 61
	v_writelane_b32 v255, s47, 1
	v_writelane_b32 v254, s44, 62
	v_writelane_b32 v255, s48, 2
	v_writelane_b32 v254, s45, 63
	v_writelane_b32 v255, s49, 3
	v_writelane_b32 v255, s50, 4
	v_readlane_b32 s2, v254, 52
	v_writelane_b32 v255, s51, 5
	s_cmp_gt_i32 s2, 0x827f
	v_readlane_b32 s3, v254, 53
	s_cbranch_scc1 .LBB0_90
	s_load_dwordx4 s[36:39], s[0:1], 0x140
	v_readlane_b32 s8, v254, 52
	s_mov_b32 s28, s8
	s_ashr_i32 s29, s28, 31
	s_add_i32 s8, s8, 0xffff7f80
	s_lshl_b64 s[24:25], s[28:29], 2
	s_waitcnt lgkmcnt(0)
	s_add_u32 s24, s36, s24
	s_addc_u32 s25, s37, s25
	s_load_dwordx16 s[36:51], s[0:1], 0x100
	v_readlane_b32 s26, v254, 50
	v_readlane_b32 s27, v254, 51
	s_mov_b32 s30, s26
	s_ashr_i32 s31, s26, 31
	s_lshl_b64 s[26:27], s[30:31], 2
	s_lshl_b64 s[34:35], s[28:29], 6
	s_waitcnt lgkmcnt(0)
	s_add_u32 s34, s50, s34
	v_mov_b32_e32 v3, 0
	s_addc_u32 s35, s51, s35
	s_mov_b32 s7, 0
	v_lshl_add_u64 v[4:5], s[34:35], 0, v[2:3]
	s_lshl_b64 s[36:37], s[30:31], 6
	s_mov_b32 s6, s28
	s_lshl_b64 s[34:35], s[28:29], 11
	v_readlane_b32 s9, v254, 53
	v_writelane_b32 v254, s6, 52
	s_add_u32 s34, s48, s34
	v_mbcnt_lo_u32_b32 v8, -1, 0
	v_writelane_b32 v254, s7, 53
	v_mov_b32_e32 v157, v3
	s_addc_u32 s35, s49, s35
	s_mov_b32 s6, s30
	v_mbcnt_hi_u32_b32 v8, -1, v8
	v_lshl_add_u64 v[6:7], s[34:35], 0, v[156:157]
	s_mov_b64 s[34:35], 0x400
	v_writelane_b32 v254, s6, 50
	v_and_b32_e32 v9, 64, v8
	v_cmp_gt_u32_e64 s[2:3], 16, v152
	v_cmp_eq_u32_e64 s[4:5], 0, v152
	v_lshl_add_u64 v[6:7], v[6:7], 0, s[34:35]
	v_writelane_b32 v254, s7, 51
	s_lshl_b64 s[38:39], s[30:31], 11
	v_lshlrev_b32_e32 v1, 4, v152
	v_add_u32_e32 v9, 64, v9
	v_xor_b32_e32 v10, 1, v8
	v_xor_b32_e32 v11, 2, v8
	v_xor_b32_e32 v12, 4, v8
	v_xor_b32_e32 v13, 8, v8
	v_xor_b32_e32 v14, 16, v8
	v_xor_b32_e32 v15, 32, v8
	v_mov_b32_e32 v16, 0x358637bd
	s_load_dwordx2 s[48:49], s[0:1], 0x0
	s_load_dwordx2 s[50:51], s[0:1], 0x8
	s_load_dwordx2 s[52:53], s[0:1], 0x38
	v_readlane_b32 s54, v254, 50
	s_mov_b32 s55, 1
	s_add_i32 s6, s8, 0x8080
	s_waitcnt lgkmcnt(0)
	s_mul_hi_u32 s40, s6, 0xff011
	s_mul_i32 s41, s40, 0x1010
	s_sub_i32 s41, s6, s41
	s_sub_i32 s42, s41, 16
	s_lshl_b32 s43, s40, 12
	s_add_i32 s42, s42, s43
	s_cmp_lt_i32 s41, 16
	s_cselect_b32 s42, s41, s42
	s_cselect_b32 s34, s52, s48
	s_cselect_b32 s35, s53, s49
	s_sub_i32 s43, s6, 0x8080
	s_cmp_gt_i32 s6, 0x807f
	s_cselect_b32 s42, s43, s42
	s_cselect_b32 s34, s50, s34
	s_cselect_b32 s35, s51, s35
	s_mov_b32 s43, 0
	s_lshl_b64 s[42:43], s[42:43], 12
	s_add_u32 s34, s34, s42
	s_addc_u32 s35, s35, s43
	global_load_dwordx4 v[102:105], v1, s[34:35]
	global_load_dwordx4 v[106:109], v1, s[34:35] offset:1024
	global_load_dwordx4 v[110:113], v1, s[34:35] offset:2048
	global_load_dwordx4 v[114:117], v1, s[34:35] offset:3072
.Lrw_loop:
	s_add_i32 s56, s8, s54
	s_add_i32 s6, s56, 0x8080
	s_cmp_gt_i32 s6, 0x827f
	s_cbranch_scc1 .Lrw_nonext
	s_mul_hi_u32 s40, s6, 0xff011
	s_mul_i32 s41, s40, 0x1010
	s_sub_i32 s41, s6, s41
	s_sub_i32 s42, s41, 16
	s_lshl_b32 s43, s40, 12
	s_add_i32 s42, s42, s43
	s_cmp_lt_i32 s41, 16
	s_cselect_b32 s42, s41, s42
	s_cselect_b32 s34, s52, s48
	s_cselect_b32 s35, s53, s49
	s_sub_i32 s43, s6, 0x8080
	s_cmp_gt_i32 s6, 0x807f
	s_cselect_b32 s42, s43, s42
	s_cselect_b32 s34, s50, s34
	s_cselect_b32 s35, s51, s35
	s_mov_b32 s43, 0
	s_lshl_b64 s[42:43], s[42:43], 12
	s_add_u32 s34, s34, s42
	s_addc_u32 s35, s35, s43
	global_load_dwordx4 v[118:121], v1, s[34:35]
	global_load_dwordx4 v[122:125], v1, s[34:35] offset:1024
	global_load_dwordx4 v[126:129], v1, s[34:35] offset:2048
	global_load_dwordx4 v[130:133], v1, s[34:35] offset:3072
	s_cmp_eq_u32 s55, 0
	s_cbranch_scc1 .Lrw_compute
	s_mov_b32 s55, 0
	s_waitcnt vmcnt(4)
	s_branch .Lrw_compute

; DI unsigned pk2(float lo, float hi) { unsigned r; asm volatile("v_cvt_pk_bf16_f32 %0, %1, %2" : "=v"(r) : "v"(lo), "v"(hi)); return r; }
; DI float bflo(unsigned u) { return __uint_as_float(u << 16); }
; DI float bfhi(unsigned u) { return __uint_as_float(u & 0xffff0000u); }
; DI float wave_sum(float v) {
; #pragma unroll
;     for (int o = 1; o < 64; o <<= 1) v += __shfl_xor(v, o);
;     return v;
; }
; DI void phase_prologue(const Prm& p, LAS unsigned char* lds, int tid, int lane, int wave) {
;     ...
;         for (int j = 0; j < 4; ++j) { const f32x4 v = ((const f32x4*)src)[lane + 64 * j]; u32x2 o; o.x = pk2(v.x, v.y); o.y = pk2(v.z, v.w);
;             const float a0 = bflo(o.x), a1 = bfhi(o.x), a2 = bflo(o.y), a3 = bfhi(o.y); ss += (a0 * a0 + a1 * a1) + (a2 * a2 + a3 * a3);
;             ((u32x2*)(p.XB + (size_t)row * 1024))[lane + 64 * j] = o; }
;         ss = wave_sum(ss);
;         if (lane < 16) p.SSQ[(size_t)row * 16 + lane] = lane == 0 ? ss : 0.f;
;         if (lane == 0) p.RINV[row] = rsqrtf(ss * (1.f / 1024.f) + EPSN);
;     }
.Lrw_compute:
	v_cvt_pk_bf16_f32 v134, v102, v103
	v_cvt_pk_bf16_f32 v135, v104, v105
	global_store_dwordx2 v[6:7], v[134:135], off offset:-1024
	v_lshlrev_b32_e32 v193, 16, v134
	v_and_b32_e32 v194, 0xffff0000, v134
	v_lshlrev_b32_e32 v195, 16, v135
	v_and_b32_e32 v196, 0xffff0000, v135
	v_mul_f32_e32 v194, v194, v194
	v_mul_f32_e32 v196, v196, v196
	v_fmac_f32_e32 v194, v193, v193
	v_fmac_f32_e32 v196, v195, v195
	v_add_f32_e32 v142, v194, v196
	v_cvt_pk_bf16_f32 v136, v106, v107
	v_cvt_pk_bf16_f32 v137, v108, v109
	global_store_dwordx2 v[6:7], v[136:137], off offset:-512
	v_lshlrev_b32_e32 v193, 16, v136
	v_and_b32_e32 v194, 0xffff0000, v136
	v_lshlrev_b32_e32 v195, 16, v137
	v_and_b32_e32 v196, 0xffff0000, v137
	v_mul_f32_e32 v194, v194, v194
	v_mul_f32_e32 v196, v196, v196
	v_fmac_f32_e32 v194, v193, v193
	v_fmac_f32_e32 v196, v195, v195
	v_add_f32_e32 v143, v194, v196
	v_cvt_pk_bf16_f32 v138, v110, v111
	v_cvt_pk_bf16_f32 v139, v112, v113
	global_store_dwordx2 v[6:7], v[138:139], off
	v_lshlrev_b32_e32 v193, 16, v138
	v_and_b32_e32 v194, 0xffff0000, v138
	v_lshlrev_b32_e32 v195, 16, v139
	v_and_b32_e32 v196, 0xffff0000, v139
	v_mul_f32_e32 v194, v194, v194
	v_mul_f32_e32 v196, v196, v196
	v_fmac_f32_e32 v194, v193, v193
	v_fmac_f32_e32 v196, v195, v195
	v_add_f32_e32 v144, v194, v196
	v_cvt_pk_bf16_f32 v140, v114, v115
	v_cvt_pk_bf16_f32 v141, v116, v117
	global_store_dwordx2 v[6:7], v[140:141], off offset:512
	v_lshlrev_b32_e32 v193, 16, v140
	v_and_b32_e32 v194, 0xffff0000, v140
	v_lshlrev_b32_e32 v195, 16, v141
	v_and_b32_e32 v196, 0xffff0000, v141
	v_mul_f32_e32 v194, v194, v194
	v_mul_f32_e32 v196, v196, v196
	v_fmac_f32_e32 v194, v193, v193
	v_fmac_f32_e32 v196, v195, v195
	v_add_f32_e32 v192, v194, v196
	v_add_f32_e32 v142, v142, v143
	v_add_f32_e32 v142, v142, v144
	v_add_f32_e32 v20, v142, v192
	v_cmp_lt_i32_e32 vcc, v10, v9
	s_nop 1
	v_cndmask_b32_e32 v21, v8, v10, vcc
	v_lshlrev_b32_e32 v21, 2, v21
	ds_bpermute_b32 v17, v21, v20
	s_waitcnt lgkmcnt(0)
	v_add_f32_e32 v20, v20, v17
	v_cmp_lt_i32_e32 vcc, v11, v9
	s_nop 1
	v_cndmask_b32_e32 v21, v8, v11, vcc
	v_lshlrev_b32_e32 v21, 2, v21
	ds_bpermute_b32 v17, v21, v20
	s_waitcnt lgkmcnt(0)
	v_add_f32_e32 v20, v20, v17
	v_cmp_lt_i32_e32 vcc, v12, v9
	s_nop 1
	v_cndmask_b32_e32 v21, v8, v12, vcc
	v_lshlrev_b32_e32 v21, 2, v21
	ds_bpermute_b32 v17, v21, v20
	s_waitcnt lgkmcnt(0)
	v_add_f32_e32 v20, v20, v17
	v_cmp_lt_i32_e32 vcc, v13, v9
	s_nop 1
	v_cndmask_b32_e32 v21, v8, v13, vcc
	v_lshlrev_b32_e32 v21, 2, v21
	ds_bpermute_b32 v17, v21, v20
	s_waitcnt lgkmcnt(0)
	v_add_f32_e32 v20, v20, v17
	v_cmp_lt_i32_e32 vcc, v14, v9
	s_nop 1
	v_cndmask_b32_e32 v21, v8, v14, vcc
	v_lshlrev_b32_e32 v21, 2, v21
	ds_bpermute_b32 v17, v21, v20
	s_waitcnt lgkmcnt(0)
	v_add_f32_e32 v20, v20, v17
	v_cmp_lt_i32_e32 vcc, v15, v9
	s_nop 1
	v_cndmask_b32_e32 v21, v8, v15, vcc
	v_lshlrev_b32_e32 v21, 2, v21
	ds_bpermute_b32 v17, v21, v20
	s_waitcnt lgkmcnt(0)
	v_add_f32_e32 v20, v20, v17
	v_mov_b32_e32 v17, v20
	s_mov_b64 s[44:45], exec
	s_and_b64 exec, s[44:45], s[2:3]
	v_cndmask_b32_e64 v18, 0, v17, s[4:5]
	global_store_dword v[4:5], v18, off
	s_mov_b64 exec, s[44:45]
	v_fmamk_f32 v17, v17, 0x3a800000, v16
	s_mov_b32 s40, 0x800000
	v_cmp_gt_f32_e32 vcc, s40, v17
	v_mul_f32_e32 v18, 0x4b800000, v17
	s_nop 1
	v_cndmask_b32_e32 v17, v17, v18, vcc
	v_rsq_f32_e32 v17, v17
	s_nop 0
	v_mul_f32_e32 v18, 0x45800000, v17
	v_cndmask_b32_e32 v17, v17, v18, vcc
	s_and_b64 exec, s[44:45], s[4:5]
	global_store_dword v3, v17, s[24:25]
	s_mov_b64 exec, s[44:45]
	s_add_u32 s24, s24, s26
	s_addc_u32 s25, s25, s27
	v_lshl_add_u64 v[4:5], v[4:5], 0, s[36:37]
	v_lshl_add_u64 v[6:7], v[6:7], 0, s[38:39]
	s_mov_b32 s8, s56
	s_add_i32 s6, s8, 0x8080
	s_cmp_gt_i32 s6, 0x827f
	s_cbranch_scc1 .Lrw_done
	s_waitcnt vmcnt(6)
	v_mov_b64_e32 v[102:103], v[118:119]
	v_mov_b64_e32 v[104:105], v[120:121]
	v_mov_b64_e32 v[106:107], v[122:123]
	v_mov_b64_e32 v[108:109], v[124:125]
	v_mov_b64_e32 v[110:111], v[126:127]
	v_mov_b64_e32 v[112:113], v[128:129]
	v_mov_b64_e32 v[114:115], v[130:131]
	v_mov_b64_e32 v[116:117], v[132:133]
	s_branch .Lrw_loop
.Lrw_done:
	v_readlane_b32 s28, v254, 50
	v_readlane_b32 s29, v254, 51
